# speedup vs baseline: 1.0172x; 1.0172x over previous
; __device__ __forceinline__ float bf2f(bf16_t h) { return __uint_as_float(((unsigned)h) << 16); }
; __device__ __forceinline__ bf16_t f2bf(float f) { return (bf16_t)(pack2(f, 0.0f) & 0xFFFFu); }
; __device__ __forceinline__ int otid() { int t = threadIdx.x; asm volatile("" : "+v"(t)); return t; }
; __device__ __forceinline__ void rowpass_mla(const Params& p, int j) {
;     const int tid_ = otid(); const int lane = tid_ & 63, w = tid_ >> 6;
;     const bf16_t* cin = (const bf16_t*)(p.ws + OFF_Q);
;     bf16_t* cqn = (bf16_t*)(p.ws + OFF_CQN); bf16_t* ckvn = (bf16_t*)(p.ws + OFF_CKVN); bf16_t* krope = (bf16_t*)(p.ws + OFF_KROPE);
;     const float* gq = p.in[4] + j * 384; const float* gkv = p.in[5] + j * 256;
;     const float* ct = (const float*)(p.ws + OFF_COS); const float* st = (const float*)(p.ws + OFF_SIN);
;     for (int row = blockIdx.x * 8 + w; row < T; row += gridDim.x * 8) {
;         const bf16_t* cp = cin + (size_t)row * 768;
;         int pos = row % L;
;         float a[6]; float ss = 0.f;
; #pragma unroll
;         for (int i = 0; i < 6; ++i) { a[i] = bf2f(cp[lane + 64 * i]); ss += a[i] * a[i]; }
;         ss = wave_sum(ss);
;         float r = rsqrtf(ss * (1.0f / 384.0f) + EPS);
; #pragma unroll
;         for (int i = 0; i < 6; ++i) cqn[(size_t)row * 384 + lane + 64 * i] = f2bf(a[i] * r * gq[lane + 64 * i]);
;         float c[4]; float s2 = 0.f;
; #pragma unroll
;         for (int i = 0; i < 4; ++i) { c[i] = bf2f(cp[384 + lane + 64 * i]); s2 += c[i] * c[i]; }
;         s2 = wave_sum(s2);
;         float r2 = rsqrtf(s2 * (1.0f / 256.0f) + EPS);
; #pragma unroll
;         for (int i = 0; i < 4; ++i) ckvn[(size_t)row * 256 + lane + 64 * i] = f2bf(c[i] * r2 * gkv[lane + 64 * i]);
;         float x = bf2f(cp[640 + lane]);
;         float xo = __shfl_xor(x, 32);
;         int fi = lane & 31;
;         float cs = ct[pos * 32 + fi], sn = st[pos * 32 + fi];
;         float o = lane < 32 ? (x * cs - xo * sn) : (x * cs + xo * sn);
;         krope[(size_t)row * 64 + lane] = f2bf(o);
.LBB0_680:
	s_or_b64 exec, exec, s[0:1]
	v_mov_b32_e32 v3, v166
	s_barrier
	v_readlane_b32 s0, v252, 39
	v_ashrrev_i32_e32 v0, 6, v3
	s_nop 0
	v_add_u32_e32 v2, s0, v0
	s_movk_i32 s0, 0x4040
	v_cmp_gt_i32_e32 vcc, s0, v2
	s_and_saveexec_b64 s[2:3], vcc
	v_readlane_b32 s10, v252, 57
	v_readlane_b32 s12, v252, 55
	s_movk_i32 s6, 0x300
	s_mov_b32 s7, 0x7f807f81
	s_mov_b32 s8, 0x800000
	s_movk_i32 s9, 0x403f
	v_readlane_b32 s11, v252, 58
	v_readlane_b32 s13, v252, 56
	s_cbranch_execz .LBB0_683
	v_readlane_b32 s4, v250, 5
	v_readlane_b32 s5, v250, 6
	s_and_b64 s[0:1], s[4:5], exec
	v_readlane_b32 s68, v252, 4
	s_cselect_b32 s0, 0x400, 0
	v_readlane_b32 s78, v252, 14
	v_readlane_b32 s79, v252, 15
	s_add_u32 s0, s78, s0
	s_addc_u32 s1, s79, 0
	s_and_b64 s[4:5], s[4:5], exec
	v_readlane_b32 s76, v252, 12
	s_cselect_b32 s4, 0x600, 0
	v_readlane_b32 s77, v252, 13
	s_add_u32 s4, s76, s4
	v_and_b32_e32 v8, 63, v3
	s_addc_u32 s5, s77, 0
	v_lshlrev_b32_e32 v0, 2, v8
	global_load_dword v15, v0, s[4:5] offset:1024
	global_load_dword v16, v0, s[4:5] offset:1280
	global_load_dword v17, v0, s[4:5]
	global_load_dword v18, v0, s[4:5] offset:256
	global_load_dword v19, v0, s[4:5] offset:512
	global_load_dword v20, v0, s[4:5] offset:768
	global_load_dword v21, v0, s[0:1]
	global_load_dword v22, v0, s[0:1] offset:256
	global_load_dword v23, v0, s[0:1] offset:512
	global_load_dword v24, v0, s[0:1] offset:768
	v_and_b32_e32 v0, 64, v183
	v_add_u32_e32 v0, 64, v0
	v_xor_b32_e32 v4, 32, v183
	v_cmp_lt_i32_e32 vcc, v4, v0
	v_readlane_b32 s0, v253, 15
	v_readlane_b32 s1, v253, 16
	v_cndmask_b32_e32 v4, v183, v4, vcc
	v_lshlrev_b32_e32 v25, 2, v4
	v_xor_b32_e32 v4, 16, v183
	v_cmp_lt_i32_e32 vcc, v4, v0
	v_and_b32_e32 v31, 31, v3
	s_mov_b64 s[4:5], 0
	v_cndmask_b32_e32 v4, v183, v4, vcc
	v_lshlrev_b32_e32 v26, 2, v4
	v_xor_b32_e32 v4, 8, v183
	v_cmp_lt_i32_e32 vcc, v4, v0
	v_readlane_b32 s69, v252, 5
	v_readlane_b32 s70, v252, 6
	v_cndmask_b32_e32 v4, v183, v4, vcc
	v_lshlrev_b32_e32 v27, 2, v4
	v_xor_b32_e32 v4, 4, v183
	v_cmp_lt_i32_e32 vcc, v4, v0
	v_readlane_b32 s71, v252, 7
	v_readlane_b32 s72, v252, 8
	v_cndmask_b32_e32 v4, v183, v4, vcc
	v_lshlrev_b32_e32 v28, 2, v4
	v_xor_b32_e32 v4, 2, v183
	v_cmp_lt_i32_e32 vcc, v4, v0
	v_readlane_b32 s73, v252, 9
	v_readlane_b32 s74, v252, 10
	v_cndmask_b32_e32 v4, v183, v4, vcc
	v_lshlrev_b32_e32 v29, 2, v4
	v_xor_b32_e32 v4, 1, v183
	v_cmp_lt_i32_e32 vcc, v4, v0
	v_readlane_b32 s75, v252, 11
	v_readlane_b32 s80, v252, 16
	v_cndmask_b32_e32 v0, v183, v4, vcc
	v_lshlrev_b32_e32 v30, 2, v0
	v_lshlrev_b32_e32 v0, 1, v8
	v_lshl_add_u64 v[6:7], s[0:1], 0, v[0:1]
	v_readlane_b32 s0, v253, 13
	v_readlane_b32 s1, v253, 14
	v_lshl_add_u64 v[4:5], s[30:31], 0, v[0:1]
	v_cmp_gt_u32_e32 vcc, 32, v8
	v_lshl_add_u64 v[8:9], s[0:1], 0, v[0:1]
	v_lshl_add_u64 v[10:11], s[24:25], 0, v[0:1]
	v_readlane_b32 s81, v252, 17
	v_readlane_b32 s82, v252, 18
	v_readlane_b32 s83, v252, 19
	v_mad_i64_i32 v[66:67], s[0:1], v2, s40, v[10:11]
	global_load_ushort v40, v[66:67], off
	global_load_ushort v41, v[66:67], off offset:128
	global_load_ushort v42, v[66:67], off offset:256
	global_load_ushort v43, v[66:67], off offset:384
	global_load_ushort v44, v[66:67], off offset:512
	global_load_ushort v45, v[66:67], off offset:640
	global_load_ushort v46, v[66:67], off offset:768
	global_load_ushort v47, v[66:67], off offset:896
	global_load_ushort v48, v[66:67], off offset:1024
	global_load_ushort v49, v[66:67], off offset:1152
	global_load_ushort v50, v[66:67], off offset:1280
	v_mul_hi_i32 v68, v2, s7
	v_lshrrev_b32_e32 v69, 31, v68
	v_ashrrev_i32_e32 v68, 11, v68
	v_add_u32_e32 v68, v68, v69
	v_mul_i32_i24_e32 v68, 0x1010, v68
	v_sub_u32_e32 v68, v2, v68
	v_lshl_or_b32 v68, v68, 5, v31
	v_ashrrev_i32_e32 v69, 31, v68
	v_lshlrev_b64 v[68:69], 2, v[68:69]
	v_lshl_add_u64 v[70:71], s[10:11], 0, v[68:69]
	global_load_dword v51, v[70:71], off
	v_lshl_add_u64 v[70:71], s[12:13], 0, v[68:69]
	global_load_dword v52, v[70:71], off
	s_waitcnt vmcnt(0)
; __device__ __forceinline__ float bf2f(bf16_t h) { return __uint_as_float(((unsigned)h) << 16); }
; __device__ __forceinline__ bf16_t f2bf(float f) { return (bf16_t)(pack2(f, 0.0f) & 0xFFFFu); }
; __device__ __forceinline__ void rowpass_mla(const Params& p, int j) {
;     ...
;     for (int row = blockIdx.x * 8 + w; row < T; row += gridDim.x * 8) {
;         const bf16_t* cp = cin + (size_t)row * 768;
;         int pos = row % L;
;         float a[6]; float ss = 0.f;
; #pragma unroll
;         for (int i = 0; i < 6; ++i) { a[i] = bf2f(cp[lane + 64 * i]); ss += a[i] * a[i]; }
;         ss = wave_sum(ss);
;         float r = rsqrtf(ss * (1.0f / 384.0f) + EPS);
; #pragma unroll
;         for (int i = 0; i < 6; ++i) cqn[(size_t)row * 384 + lane + 64 * i] = f2bf(a[i] * r * gq[lane + 64 * i]);
;         float c[4]; float s2 = 0.f;
; #pragma unroll
;         for (int i = 0; i < 4; ++i) { c[i] = bf2f(cp[384 + lane + 64 * i]); s2 += c[i] * c[i]; }
;         s2 = wave_sum(s2);
;         float r2 = rsqrtf(s2 * (1.0f / 256.0f) + EPS);
; #pragma unroll
;         for (int i = 0; i < 4; ++i) ckvn[(size_t)row * 256 + lane + 64 * i] = f2bf(c[i] * r2 * gkv[lane + 64 * i]);
;         float x = bf2f(cp[640 + lane]);
;         float xo = __shfl_xor(x, 32);
;         int fi = lane & 31;
;         float cs = ct[pos * 32 + fi], sn = st[pos * 32 + fi];
;         float o = lane < 32 ? (x * cs - xo * sn) : (x * cs + xo * sn);
;         krope[(size_t)row * 64 + lane] = f2bf(o);
;     }
.LBB0_682:
	v_add_u32_e32 v72, s66, v2
	v_min_i32_e32 v72, s9, v72
	v_mad_i64_i32 v[66:67], s[0:1], v72, s40, v[10:11]
	global_load_ushort v53, v[66:67], off
	global_load_ushort v54, v[66:67], off offset:128
	global_load_ushort v55, v[66:67], off offset:256
	global_load_ushort v56, v[66:67], off offset:384
	global_load_ushort v57, v[66:67], off offset:512
	global_load_ushort v58, v[66:67], off offset:640
	global_load_ushort v59, v[66:67], off offset:768
	global_load_ushort v60, v[66:67], off offset:896
	global_load_ushort v61, v[66:67], off offset:1024
	global_load_ushort v62, v[66:67], off offset:1152
	global_load_ushort v63, v[66:67], off offset:1280
	v_mul_hi_i32 v68, v72, s7
	v_lshrrev_b32_e32 v69, 31, v68
	v_ashrrev_i32_e32 v68, 11, v68
	v_add_u32_e32 v68, v68, v69
	v_mul_i32_i24_e32 v68, 0x1010, v68
	v_sub_u32_e32 v68, v72, v68
	v_lshl_or_b32 v68, v68, 5, v31
	v_ashrrev_i32_e32 v69, 31, v68
	v_lshlrev_b64 v[68:69], 2, v[68:69]
	v_lshl_add_u64 v[70:71], s[10:11], 0, v[68:69]
	global_load_dword v64, v[70:71], off
	v_lshl_add_u64 v[70:71], s[12:13], 0, v[68:69]
	global_load_dword v65, v[70:71], off
	v_ashrrev_i32_e32 v3, 31, v2
	v_lshlrev_b32_e32 v0, 16, v40
	v_lshlrev_b32_e32 v38, 16, v41
	v_mul_f32_e32 v36, v38, v38
	v_fmac_f32_e32 v36, v0, v0
	v_lshlrev_b32_e32 v32, 16, v42
	v_lshlrev_b32_e32 v33, 16, v43
	v_pk_mul_f32 v[34:35], v[32:33], v[32:33]
	s_nop 0
	v_add_f32_e32 v34, v36, v34
	v_add_f32_e32 v39, v34, v35
	v_lshlrev_b32_e32 v34, 16, v44
	v_lshlrev_b32_e32 v35, 16, v45
	v_pk_mul_f32 v[36:37], v[34:35], v[34:35]
	s_nop 0
	v_add_f32_e32 v36, v39, v36
	v_add_f32_e32 v36, v36, v37
	ds_bpermute_b32 v37, v25, v36
	s_waitcnt lgkmcnt(0)
	v_add_f32_e32 v36, v36, v37
	ds_bpermute_b32 v37, v26, v36
	s_waitcnt lgkmcnt(0)
	v_add_f32_e32 v36, v36, v37
	ds_bpermute_b32 v37, v27, v36
	s_waitcnt lgkmcnt(0)
	v_add_f32_e32 v36, v36, v37
	ds_bpermute_b32 v37, v28, v36
	s_waitcnt lgkmcnt(0)
	v_add_f32_e32 v36, v36, v37
	ds_bpermute_b32 v37, v29, v36
	s_waitcnt lgkmcnt(0)
	v_add_f32_e32 v36, v36, v37
	ds_bpermute_b32 v37, v30, v36
	s_waitcnt lgkmcnt(0)
	v_add_f32_e32 v36, v36, v37
	v_fmamk_f32 v36, v36, 0x3b2aaaab, v174
	v_cmp_gt_f32_e64 s[0:1], s8, v36
	v_mul_f32_e32 v37, 0x4b800000, v36
	s_nop 0
	v_cndmask_b32_e64 v36, v36, v37, s[0:1]
	v_rsq_f32_e32 v36, v36
	s_nop 0
	v_mul_f32_e32 v37, 0x45800000, v36
	v_cndmask_b32_e64 v39, v36, v37, s[0:1]
	v_mul_f32_e32 v0, v39, v0
	v_mad_i64_i32 v[36:37], s[0:1], v2, s6, v[4:5]
	v_mul_f32_e32 v0, v17, v0
	s_nop 0
	v_cvt_pk_bf16_f32 v0, v0, s0
	global_store_short v[36:37], v0, off
	v_mul_f32_e32 v0, v39, v38
	v_mul_f32_e32 v0, v18, v0
	v_cvt_pk_bf16_f32 v0, v0, s0
	global_store_short v[36:37], v0, off offset:128
	v_mul_f32_e32 v0, v39, v32
	v_mul_f32_e32 v0, v19, v0
	v_cvt_pk_bf16_f32 v0, v0, s0
	global_store_short v[36:37], v0, off offset:256
	v_mul_f32_e32 v0, v39, v33
	v_mul_f32_e32 v0, v20, v0
	v_cvt_pk_bf16_f32 v0, v0, s0
	global_store_short v[36:37], v0, off offset:384
	v_mul_f32_e32 v0, v39, v34
	v_mul_f32_e32 v0, v15, v0
	v_cvt_pk_bf16_f32 v0, v0, s0
	global_store_short v[36:37], v0, off offset:512
	v_mul_f32_e32 v0, v39, v35
	v_mul_f32_e32 v0, v16, v0
	v_cvt_pk_bf16_f32 v0, v0, s0
	global_store_short v[36:37], v0, off offset:640
	v_lshlrev_b32_e32 v33, 16, v47
	v_lshlrev_b32_e32 v32, 16, v46
	v_pk_mul_f32 v[34:35], v[32:33], v[32:33]
	v_lshlrev_b32_e32 v37, 16, v49
	v_lshlrev_b32_e32 v36, 16, v48
	v_pk_mul_f32 v[38:39], v[36:37], v[36:37]
	v_add_f32_e32 v0, v34, v35
	v_add_f32_e32 v0, v0, v38
	v_add_f32_e32 v0, v0, v39
	ds_bpermute_b32 v34, v25, v0
	s_waitcnt lgkmcnt(0)
	v_add_f32_e32 v0, v0, v34
	ds_bpermute_b32 v34, v26, v0
	s_waitcnt lgkmcnt(0)
	v_add_f32_e32 v0, v0, v34
	ds_bpermute_b32 v34, v27, v0
	s_waitcnt lgkmcnt(0)
	v_add_f32_e32 v0, v0, v34
	ds_bpermute_b32 v34, v28, v0
	s_waitcnt lgkmcnt(0)
	v_add_f32_e32 v0, v0, v34
	ds_bpermute_b32 v34, v29, v0
	s_waitcnt lgkmcnt(0)
	v_add_f32_e32 v0, v0, v34
	ds_bpermute_b32 v34, v30, v0
	s_waitcnt lgkmcnt(0)
	v_add_f32_e32 v0, v0, v34
	v_fmamk_f32 v0, v0, 0x3b800000, v174
	v_cmp_gt_f32_e64 s[0:1], s8, v0
	v_mul_f32_e32 v34, 0x4b800000, v0
	s_nop 0
	v_cndmask_b32_e64 v0, v0, v34, s[0:1]
	v_rsq_f32_e32 v0, v0
	s_nop 0
	v_mul_f32_e32 v34, 0x45800000, v0
	v_cndmask_b32_e64 v0, v0, v34, s[0:1]
	v_mul_f32_e32 v32, v0, v32
	v_lshlrev_b64 v[34:35], 9, v[2:3]
	v_mul_f32_e32 v32, v21, v32
	v_lshl_add_u64 v[34:35], v[6:7], 0, v[34:35]
	v_cvt_pk_bf16_f32 v32, v32, s0
	global_store_short v[34:35], v32, off
	v_mul_f32_e32 v32, v0, v33
	v_mul_f32_e32 v32, v22, v32
	v_cvt_pk_bf16_f32 v32, v32, s0
	global_store_short v[34:35], v32, off offset:128
	v_mul_f32_e32 v32, v0, v36
	v_mul_f32_e32 v32, v23, v32
	v_cvt_pk_bf16_f32 v32, v32, s0
	global_store_short v[34:35], v32, off offset:256
	v_mul_f32_e32 v0, v0, v37
	v_mul_f32_e32 v0, v24, v0
	v_cvt_pk_bf16_f32 v0, v0, s0
	global_store_short v[34:35], v0, off offset:384
	v_lshlrev_b32_e32 v34, 16, v50
	s_nop 0
	ds_bpermute_b32 v35, v25, v34
	s_waitcnt lgkmcnt(0)
	v_mul_f32_e32 v12, v52, v35
	v_cndmask_b32_e64 v12, v12, -v12, vcc
	v_fmac_f32_e32 v12, v51, v34
	v_cvt_pk_bf16_f32 v0, v12, s0
	v_lshlrev_b64 v[12:13], 7, v[2:3]
	v_lshl_add_u64 v[12:13], v[8:9], 0, v[12:13]
	global_store_short v[12:13], v0, off
	s_waitcnt vmcnt(11)
	v_mov_b32_e32 v40, v53
	v_mov_b32_e32 v41, v54
	v_mov_b32_e32 v42, v55
	v_mov_b32_e32 v43, v56
	v_mov_b32_e32 v44, v57
	v_mov_b32_e32 v45, v58
	v_mov_b32_e32 v46, v59
	v_mov_b32_e32 v47, v60
	v_mov_b32_e32 v48, v61
	v_mov_b32_e32 v49, v62
	v_mov_b32_e32 v50, v63
	v_mov_b32_e32 v51, v64
	v_mov_b32_e32 v52, v65
	v_add_u32_e32 v2, s66, v2
	v_cmp_lt_i32_e64 s[0:1], s9, v2
	s_or_b64 s[4:5], s[0:1], s[4:5]
	s_andn2_b64 exec, exec, s[4:5]
	s_cbranch_execnz .LBB0_682

; template <int EPI, int AMAP, int KOFFMODE, int K>
; __device__ __forceinline__ void gemm_phase(unsigned char* smem, const bf16_t* A, int lda, const bf16_t* Bt, int NT, const EpiArgs& ea) {
;     ...
;         f32x16 acc[4][2];
; #pragma unroll
;         for (int i = 0; i < 4; ++i)
; #pragma unroll
;             for (int j = 0; j < 2; ++j)
; #pragma unroll
;                 for (int r = 0; r < 16; ++r) acc[i][j][r] = 0.f;
;         for (int kt = 0; kt < nk; ++kt) {
;             if (kt + 1 < nk) GEMM_DMA(m0, n0, kt + 1, cur ^ 1);
;             else if (have_next) GEMM_DMA(m0n, n0n, 0, cur ^ 1);
;             const unsigned char* Ac = smem + cur * STGB + (wm * 128 + l31) * 128;
;             const unsigned char* Bc = smem + cur * STGB + 32768 + (wn * 64 + l31) * 128;
;             bf16x8 fa[2][4], fb[2][2];
;             fb[0][0] = *(const bf16x8*)(Bc + (((0) ^ yz) & 7) * 16);
;             fb[0][1] = *(const bf16x8*)(Bc + 32 * 128 + (((0) ^ yz) & 7) * 16);
; #pragma unroll
;             for (int i = 0; i < 4; ++i) fa[0][i] = *(const bf16x8*)(Ac + i * 32 * 128 + (((0) ^ yz) & 7) * 16);
; #pragma unroll
;             for (int s = 0; s < 4; ++s) {
;                 if (s < 3) {
;                     const int o_ = (((2 * (s + 1)) ^ yz) & 7) * 16;
;                     fb[(s + 1) & 1][0] = *(const bf16x8*)(Bc + o_);
;                     fb[(s + 1) & 1][1] = *(const bf16x8*)(Bc + 32 * 128 + o_);
; #pragma unroll
;                     for (int i = 0; i < 4; ++i) fa[(s + 1) & 1][i] = *(const bf16x8*)(Ac + i * 32 * 128 + o_);
;                 }
; #pragma unroll
;                 for (int i = 0; i < 4; ++i) {
;                     acc[i][0] = __builtin_amdgcn_mfma_f32_32x32x16_bf16(fa[s & 1][i], fb[s & 1][0], acc[i][0], 0, 0, 0);
;                     acc[i][1] = __builtin_amdgcn_mfma_f32_32x32x16_bf16(fa[s & 1][i], fb[s & 1][1], acc[i][1], 0, 0, 0);
;                 }
;                 __builtin_amdgcn_sched_barrier(0);
;             }
;             if (kt + 1 < nk) asm volatile("s_waitcnt vmcnt(0)" ::: "memory");
;             __builtin_amdgcn_s_barrier();
;             cur ^= 1;
;         }
.LBB0_1031:
	v_add_u32_e32 v2, s12, v143
	v_ashrrev_i32_e32 v3, 31, v2
	v_lshlrev_b64 v[2:3], 11, v[2:3]
	v_lshl_add_u64 v[136:137], v[134:135], 0, v[2:3]
	v_add_u32_e32 v2, s13, v143
	v_ashrrev_i32_e32 v3, 31, v2
	v_lshlrev_b64 v[2:3], 11, v[2:3]
	v_lshl_add_u64 v[138:139], v[134:135], 0, v[2:3]
	v_mov_b32_e32 v2, 0
	s_mov_b64 s[4:5], 0
	s_mov_b32 s15, s11
	v_mov_b32_e32 v3, v2
	v_mov_b32_e32 v4, v2
	v_mov_b32_e32 v5, v2
	v_mov_b32_e32 v6, v2
	v_mov_b32_e32 v7, v2
	v_mov_b32_e32 v8, v2
	v_mov_b32_e32 v9, v2
	v_mov_b32_e32 v10, v2
	v_mov_b32_e32 v11, v2
	v_mov_b32_e32 v12, v2
	v_mov_b32_e32 v13, v2
	v_mov_b32_e32 v14, v2
	v_mov_b32_e32 v15, v2
	v_mov_b32_e32 v16, v2
	v_mov_b32_e32 v17, v2
	v_mov_b32_e32 v18, v2
	v_mov_b32_e32 v19, v2
	v_mov_b32_e32 v20, v2
	v_mov_b32_e32 v21, v2
	v_mov_b32_e32 v22, v2
	v_mov_b32_e32 v23, v2
	v_mov_b32_e32 v24, v2
	v_mov_b32_e32 v25, v2
	v_mov_b32_e32 v26, v2
	v_mov_b32_e32 v27, v2
	v_mov_b32_e32 v28, v2
	v_mov_b32_e32 v29, v2
	v_mov_b32_e32 v30, v2
	v_mov_b32_e32 v31, v2
	v_mov_b32_e32 v32, v2
	v_mov_b32_e32 v33, v2
	v_mov_b32_e32 v34, v2
	v_mov_b32_e32 v35, v2
	v_mov_b32_e32 v36, v2
	v_mov_b32_e32 v37, v2
	v_mov_b32_e32 v38, v2
	v_mov_b32_e32 v39, v2
	v_mov_b32_e32 v40, v2
	v_mov_b32_e32 v41, v2
	v_mov_b32_e32 v42, v2
	v_mov_b32_e32 v43, v2
	v_mov_b32_e32 v44, v2
	v_mov_b32_e32 v45, v2
	v_mov_b32_e32 v46, v2
	v_mov_b32_e32 v47, v2
	v_mov_b32_e32 v48, v2
	v_mov_b32_e32 v49, v2
	v_mov_b32_e32 v50, v2
	v_mov_b32_e32 v51, v2
	v_mov_b32_e32 v52, v2
	v_mov_b32_e32 v53, v2
	v_mov_b32_e32 v54, v2
	v_mov_b32_e32 v55, v2
	v_mov_b32_e32 v56, v2
	v_mov_b32_e32 v57, v2
	v_mov_b32_e32 v58, v2
	v_mov_b32_e32 v59, v2
	v_mov_b32_e32 v60, v2
	v_mov_b32_e32 v61, v2
	v_mov_b32_e32 v62, v2
	v_mov_b32_e32 v63, v2
	v_mov_b32_e32 v64, v2
	v_mov_b32_e32 v65, v2
	v_mov_b32_e32 v66, v2
	v_mov_b32_e32 v67, v2
	v_mov_b32_e32 v68, v2
	v_mov_b32_e32 v69, v2
	v_mov_b32_e32 v70, v2
	v_mov_b32_e32 v71, v2
	v_mov_b32_e32 v72, v2
	v_mov_b32_e32 v73, v2
	v_mov_b32_e32 v74, v2
	v_mov_b32_e32 v75, v2
	v_mov_b32_e32 v76, v2
	v_mov_b32_e32 v77, v2
	v_mov_b32_e32 v78, v2
	v_mov_b32_e32 v79, v2
	v_mov_b32_e32 v80, v2
	v_mov_b32_e32 v81, v2
	v_mov_b32_e32 v82, v2
	v_mov_b32_e32 v83, v2
	v_mov_b32_e32 v84, v2
	v_mov_b32_e32 v85, v2
	v_mov_b32_e32 v86, v2
	v_mov_b32_e32 v87, v2
	v_mov_b32_e32 v88, v2
	v_mov_b32_e32 v89, v2
	v_mov_b32_e32 v90, v2
	v_mov_b32_e32 v91, v2
	v_mov_b32_e32 v92, v2
	v_mov_b32_e32 v93, v2
	v_mov_b32_e32 v94, v2
	v_mov_b32_e32 v95, v2
	v_mov_b32_e32 v96, v2
	v_mov_b32_e32 v97, v2
	v_mov_b32_e32 v98, v2
	v_mov_b32_e32 v99, v2
	v_mov_b32_e32 v100, v2
	v_mov_b32_e32 v101, v2
	v_mov_b32_e32 v102, v2
	v_mov_b32_e32 v103, v2
	v_mov_b32_e32 v104, v2
	v_mov_b32_e32 v105, v2
	v_mov_b32_e32 v106, v2
	v_mov_b32_e32 v107, v2
	v_mov_b32_e32 v108, v2
	v_mov_b32_e32 v109, v2
	v_mov_b32_e32 v110, v2
	v_mov_b32_e32 v111, v2
	v_mov_b32_e32 v112, v2
	v_mov_b32_e32 v113, v2
	v_mov_b32_e32 v114, v2
	v_mov_b32_e32 v115, v2
	v_mov_b32_e32 v116, v2
	v_mov_b32_e32 v117, v2
	v_mov_b32_e32 v118, v2
	v_mov_b32_e32 v119, v2
	v_mov_b32_e32 v120, v2
	v_mov_b32_e32 v121, v2
	v_mov_b32_e32 v122, v2
	v_mov_b32_e32 v123, v2
	v_mov_b32_e32 v124, v2
	v_mov_b32_e32 v125, v2
	v_mov_b32_e32 v126, v2
	v_mov_b32_e32 v127, v2
	v_mov_b32_e32 v128, v2
	v_mov_b32_e32 v129, v2
	s_mov_b64 s[20:21], 0x2000080
	s_mov_b64 vcc, 0x2020080
	s_mov_b64 s[68:69], 0x2040080
	s_lshl_b32 s28, s15, 16
	v_add3_u32 v191, s28, v151, v150
	v_add_u32_e32 v191, v191, v152
	v_add3_u32 v0, s28, v149, v150
	v_add_u32_e32 v0, v0, v152
	ds_read_b128 v[156:159], v191 offset:32768
	ds_read_b128 v[160:163], v191 offset:36864
	ds_read_b128 v[192:195], v0
	ds_read_b128 v[196:199], v0 offset:4096
	ds_read_b128 v[200:203], v0 offset:8192
	ds_read_b128 v[204:207], v0 offset:12288
.LBB0_1032:
	s_mov_b32 s11, s15
	s_lshl_b32 s15, s11, 16
	s_xor_b32 s14, s15, 0x10000
	v_readfirstlane_b32 s28, v144
	s_nop 0
	s_add_u32 s28, s28, s14
	v_add3_u32 v191, s15, v151, v150
	v_add_u32_e32 v191, v191, v153
	v_add3_u32 v0, s15, v149, v150
	v_add_u32_e32 v0, v0, v153
	ds_read_b128 v[208:211], v191 offset:32768
	ds_read_b128 v[212:215], v191 offset:36864
	s_waitcnt lgkmcnt(5)
	v_mfma_f32_32x32x16_bf16 v[114:129], v[192:195], v[156:159], v[114:129]
	s_add_u32 s34, s4, s20
	s_addc_u32 s35, s5, s21
	s_mov_b32 m0, s28
	v_lshl_add_u64 v[164:165], v[136:137], 0, s[34:35]
	global_load_lds_dwordx4 v[164:165], off
	v_mfma_f32_32x32x16_bf16 v[98:113], v[192:195], v[160:163], v[98:113]
	s_add_u32 s34, s4, vcc_lo
	s_addc_u32 s35, s5, vcc_hi
	s_add_u32 m0, s28, 0x2000
	v_lshl_add_u64 v[164:165], v[136:137], 0, s[34:35]
	global_load_lds_dwordx4 v[164:165], off
	ds_read_b128 v[192:195], v0
	s_waitcnt lgkmcnt(5)
	v_mfma_f32_32x32x16_bf16 v[82:97], v[196:199], v[156:159], v[82:97]
	s_add_u32 s34, s4, s68
	s_addc_u32 s35, s5, s69
	s_add_u32 m0, s28, 0x4000
	v_lshl_add_u64 v[164:165], v[136:137], 0, s[34:35]
	global_load_lds_dwordx4 v[164:165], off
	v_mfma_f32_32x32x16_bf16 v[66:81], v[196:199], v[160:163], v[66:81]
	s_add_u32 s34, s4, s88
	s_addc_u32 s35, s5, s89
	s_add_u32 m0, s28, 0x6000
	v_lshl_add_u64 v[164:165], v[136:137], 0, s[34:35]
	global_load_lds_dwordx4 v[164:165], off
	ds_read_b128 v[196:199], v0 offset:4096
	s_waitcnt lgkmcnt(5)
	v_mfma_f32_32x32x16_bf16 v[50:65], v[200:203], v[156:159], v[50:65]
	s_add_u32 s34, s4, 0xe00080
	s_addc_u32 s35, s5, 0
	s_add_u32 m0, s28, 0x8000
	v_lshl_add_u64 v[164:165], v[138:139], 0, s[34:35]
	global_load_lds_dwordx4 v[164:165], off
	v_mfma_f32_32x32x16_bf16 v[34:49], v[200:203], v[160:163], v[34:49]
	s_add_u32 s34, s4, 0xe20080
	s_addc_u32 s35, s5, 0
	s_add_u32 m0, s28, 0xa000
	v_lshl_add_u64 v[164:165], v[138:139], 0, s[34:35]
	global_load_lds_dwordx4 v[164:165], off
	ds_read_b128 v[200:203], v0 offset:8192
	s_waitcnt lgkmcnt(5)
; template <int EPI, int AMAP, int KOFFMODE, int K>
; __device__ __forceinline__ void gemm_phase(unsigned char* smem, const bf16_t* A, int lda, const bf16_t* Bt, int NT, const EpiArgs& ea) {
;     ...
;         for (int kt = 0; kt < nk; ++kt) {
;             if (kt + 1 < nk) GEMM_DMA(m0, n0, kt + 1, cur ^ 1);
;             else if (have_next) GEMM_DMA(m0n, n0n, 0, cur ^ 1);
;             const unsigned char* Ac = smem + cur * STGB + (wm * 128 + l31) * 128;
;             const unsigned char* Bc = smem + cur * STGB + 32768 + (wn * 64 + l31) * 128;
;             bf16x8 fa[2][4], fb[2][2];
;             fb[0][0] = *(const bf16x8*)(Bc + (((0) ^ yz) & 7) * 16);
;             fb[0][1] = *(const bf16x8*)(Bc + 32 * 128 + (((0) ^ yz) & 7) * 16);
; #pragma unroll
;             for (int i = 0; i < 4; ++i) fa[0][i] = *(const bf16x8*)(Ac + i * 32 * 128 + (((0) ^ yz) & 7) * 16);
; #pragma unroll
;             for (int s = 0; s < 4; ++s) {
;                 if (s < 3) {
;                     const int o_ = (((2 * (s + 1)) ^ yz) & 7) * 16;
;                     fb[(s + 1) & 1][0] = *(const bf16x8*)(Bc + o_);
;                     fb[(s + 1) & 1][1] = *(const bf16x8*)(Bc + 32 * 128 + o_);
; #pragma unroll
;                     for (int i = 0; i < 4; ++i) fa[(s + 1) & 1][i] = *(const bf16x8*)(Ac + i * 32 * 128 + o_);
;                 }
; #pragma unroll
;                 for (int i = 0; i < 4; ++i) {
;                     acc[i][0] = __builtin_amdgcn_mfma_f32_32x32x16_bf16(fa[s & 1][i], fb[s & 1][0], acc[i][0], 0, 0, 0);
;                     acc[i][1] = __builtin_amdgcn_mfma_f32_32x32x16_bf16(fa[s & 1][i], fb[s & 1][1], acc[i][1], 0, 0, 0);
;                 }
;                 __builtin_amdgcn_sched_barrier(0);
;             }
;             if (kt + 1 < nk) asm volatile("s_waitcnt vmcnt(0)" ::: "memory");
;             __builtin_amdgcn_s_barrier();
;             cur ^= 1;
;         }
	v_mfma_f32_32x32x16_bf16 v[18:33], v[204:207], v[156:159], v[18:33]
	s_add_u32 s34, s4, 0xe40080
	s_addc_u32 s35, s5, 0
	s_add_u32 m0, s28, 0xc000
	v_lshl_add_u64 v[164:165], v[138:139], 0, s[34:35]
	global_load_lds_dwordx4 v[164:165], off
	v_mfma_f32_32x32x16_bf16 v[2:17], v[204:207], v[160:163], v[2:17]
	s_add_u32 s34, s4, 0xe60080
	s_addc_u32 s35, s5, 0
	s_add_u32 m0, s28, 0xe000
	v_lshl_add_u64 v[164:165], v[138:139], 0, s[34:35]
	global_load_lds_dwordx4 v[164:165], off
	ds_read_b128 v[204:207], v0 offset:12288
	v_add3_u32 v191, s15, v151, v150
	v_add_u32_e32 v191, v191, v154
	v_add3_u32 v0, s15, v149, v150
	v_add_u32_e32 v0, v0, v154
	ds_read_b128 v[156:159], v191 offset:32768
	ds_read_b128 v[160:163], v191 offset:36864
	s_waitcnt lgkmcnt(5)
	v_mfma_f32_32x32x16_bf16 v[114:129], v[192:195], v[208:211], v[114:129]
	v_mfma_f32_32x32x16_bf16 v[98:113], v[192:195], v[212:215], v[98:113]
	ds_read_b128 v[192:195], v0
	s_waitcnt lgkmcnt(5)
	v_mfma_f32_32x32x16_bf16 v[82:97], v[196:199], v[208:211], v[82:97]
	v_mfma_f32_32x32x16_bf16 v[66:81], v[196:199], v[212:215], v[66:81]
	ds_read_b128 v[196:199], v0 offset:4096
	s_waitcnt lgkmcnt(5)
	v_mfma_f32_32x32x16_bf16 v[50:65], v[200:203], v[208:211], v[50:65]
	v_mfma_f32_32x32x16_bf16 v[34:49], v[200:203], v[212:215], v[34:49]
	ds_read_b128 v[200:203], v0 offset:8192
	s_waitcnt lgkmcnt(5)
	v_mfma_f32_32x32x16_bf16 v[18:33], v[204:207], v[208:211], v[18:33]
	v_mfma_f32_32x32x16_bf16 v[2:17], v[204:207], v[212:215], v[2:17]
	ds_read_b128 v[204:207], v0 offset:12288
	v_add3_u32 v191, s15, v151, v150
	v_add_u32_e32 v191, v191, v155
	v_add3_u32 v0, s15, v149, v150
	v_add_u32_e32 v0, v0, v155
	ds_read_b128 v[208:211], v191 offset:32768
	ds_read_b128 v[212:215], v191 offset:36864
	s_waitcnt lgkmcnt(5)
	v_mfma_f32_32x32x16_bf16 v[114:129], v[192:195], v[156:159], v[114:129]
	v_mfma_f32_32x32x16_bf16 v[98:113], v[192:195], v[160:163], v[98:113]
	ds_read_b128 v[192:195], v0
	s_waitcnt lgkmcnt(5)
	v_mfma_f32_32x32x16_bf16 v[82:97], v[196:199], v[156:159], v[82:97]
	v_mfma_f32_32x32x16_bf16 v[66:81], v[196:199], v[160:163], v[66:81]
	ds_read_b128 v[196:199], v0 offset:4096
	s_waitcnt lgkmcnt(5)
	v_mfma_f32_32x32x16_bf16 v[50:65], v[200:203], v[156:159], v[50:65]
	v_mfma_f32_32x32x16_bf16 v[34:49], v[200:203], v[160:163], v[34:49]
	ds_read_b128 v[200:203], v0 offset:8192
	s_waitcnt lgkmcnt(5)
	v_mfma_f32_32x32x16_bf16 v[18:33], v[204:207], v[156:159], v[18:33]
	v_mfma_f32_32x32x16_bf16 v[2:17], v[204:207], v[160:163], v[2:17]
	ds_read_b128 v[204:207], v0 offset:12288
	s_waitcnt lgkmcnt(3)
	v_mfma_f32_32x32x16_bf16 v[114:129], v[192:195], v[208:211], v[114:129]
	v_mfma_f32_32x32x16_bf16 v[98:113], v[192:195], v[212:215], v[98:113]
	s_waitcnt lgkmcnt(0)
	s_waitcnt vmcnt(0)
	s_barrier
	v_add3_u32 v191, s14, v151, v150
	v_add_u32_e32 v191, v191, v152
	v_add3_u32 v0, s14, v149, v150
	v_add_u32_e32 v0, v0, v152
	ds_read_b128 v[156:159], v191 offset:32768
	ds_read_b128 v[160:163], v191 offset:36864
	ds_read_b128 v[192:195], v0
	v_mfma_f32_32x32x16_bf16 v[82:97], v[196:199], v[208:211], v[82:97]
	v_mfma_f32_32x32x16_bf16 v[66:81], v[196:199], v[212:215], v[66:81]
	ds_read_b128 v[196:199], v0 offset:4096
	v_mfma_f32_32x32x16_bf16 v[50:65], v[200:203], v[208:211], v[50:65]
	v_mfma_f32_32x32x16_bf16 v[34:49], v[200:203], v[212:215], v[34:49]
	ds_read_b128 v[200:203], v0 offset:8192
	v_mfma_f32_32x32x16_bf16 v[18:33], v[204:207], v[208:211], v[18:33]
	v_mfma_f32_32x32x16_bf16 v[2:17], v[204:207], v[212:215], v[2:17]
	ds_read_b128 v[204:207], v0 offset:12288
	s_xor_b32 s15, s11, 1
	s_add_u32 s4, s4, 0x80
	s_addc_u32 s5, s5, 0
	s_cmpk_eq_i32 s4, 0x780
	s_cbranch_scc0 .LBB0_1032
	s_waitcnt lgkmcnt(0)
	s_andn2_b64 vcc, exec, s[2:3]
	s_lshl_b32 s2, s15, 16
	s_cbranch_vccnz .LBB0_1024
	v_add_u32_e32 v136, s10, v143
	s_xor_b32 s3, s2, 0x10000
	v_ashrrev_i32_e32 v137, 31, v136
	v_add_u32_e32 v138, s9, v143
	v_add_u32_e32 v0, s3, v144
	v_lshlrev_b64 v[136:137], 11, v[136:137]
	v_ashrrev_i32_e32 v139, 31, v138
	v_add_u32_e32 v156, 0x8000, v0
	v_readfirstlane_b32 s3, v0
	v_lshlrev_b64 v[138:139], 11, v[138:139]
	v_lshl_add_u64 v[136:137], v[130:131], 0, v[136:137]
	s_mov_b32 m0, s3
	v_readfirstlane_b32 s3, v156
	v_add_u32_e32 v158, 0x2000, v0
	v_lshl_add_u64 v[138:139], v[132:133], 0, v[138:139]
	global_load_lds_dwordx4 v[136:137], off
	s_mov_b32 m0, s3
	s_mov_b64 s[4:5], 0x20000
	v_readfirstlane_b32 s3, v158
	v_add_u32_e32 v158, 0xa000, v0
	global_load_lds_dwordx4 v[138:139], off
	v_lshl_add_u64 v[156:157], v[136:137], 0, s[4:5]
	s_mov_b32 m0, s3
	v_readfirstlane_b32 s3, v158
	v_add_u32_e32 v158, 0x4000, v0
	global_load_lds_dwordx4 v[156:157], off
	v_lshl_add_u64 v[156:157], v[138:139], 0, s[4:5]
	s_mov_b32 m0, s3
	s_mov_b64 s[4:5], 0x40000
	v_readfirstlane_b32 s3, v158
	v_add_u32_e32 v158, 0xc000, v0
	global_load_lds_dwordx4 v[156:157], off
	v_lshl_add_u64 v[156:157], v[136:137], 0, s[4:5]
	s_mov_b32 m0, s3
	v_readfirstlane_b32 s3, v158
	global_load_lds_dwordx4 v[156:157], off
	v_lshl_add_u64 v[156:157], v[138:139], 0, s[4:5]
	s_mov_b32 m0, s3
	s_mov_b64 s[4:5], 0x60000
	global_load_lds_dwordx4 v[156:157], off
	v_add_u32_e32 v156, 0x6000, v0
	v_add_u32_e32 v0, 0xe000, v0
	v_readfirstlane_b32 s3, v156
	v_lshl_add_u64 v[136:137], v[136:137], 0, s[4:5]
	s_mov_b32 m0, s3
	v_readfirstlane_b32 s3, v0
	global_load_lds_dwordx4 v[136:137], off
	v_lshl_add_u64 v[136:137], v[138:139], 0, s[4:5]
	s_mov_b32 m0, s3
	s_nop 0
	global_load_lds_dwordx4 v[136:137], off
	s_branch .LBB0_1024

; template <int EPI, int AMAP, int KOFFMODE, int K>
; __device__ __forceinline__ void gemm_phase(unsigned char* smem, const bf16_t* A, int lda, const bf16_t* Bt, int NT, const EpiArgs& ea) {
;     ...
;         f32x16 acc[4][2];
; #pragma unroll
;         for (int i = 0; i < 4; ++i)
; #pragma unroll
;             for (int j = 0; j < 2; ++j)
; #pragma unroll
;                 for (int r = 0; r < 16; ++r) acc[i][j][r] = 0.f;
;         for (int kt = 0; kt < nk; ++kt) {
;             if (kt + 1 < nk) GEMM_DMA(m0, n0, kt + 1, cur ^ 1);
;             else if (have_next) GEMM_DMA(m0n, n0n, 0, cur ^ 1);
;             const unsigned char* Ac = smem + cur * STGB + (wm * 128 + l31) * 128;
;             const unsigned char* Bc = smem + cur * STGB + 32768 + (wn * 64 + l31) * 128;
;             bf16x8 fa[2][4], fb[2][2];
;             fb[0][0] = *(const bf16x8*)(Bc + (((0) ^ yz) & 7) * 16);
;             fb[0][1] = *(const bf16x8*)(Bc + 32 * 128 + (((0) ^ yz) & 7) * 16);
; #pragma unroll
;             for (int i = 0; i < 4; ++i) fa[0][i] = *(const bf16x8*)(Ac + i * 32 * 128 + (((0) ^ yz) & 7) * 16);
; #pragma unroll
;             for (int s = 0; s < 4; ++s) {
;                 if (s < 3) {
;                     const int o_ = (((2 * (s + 1)) ^ yz) & 7) * 16;
;                     fb[(s + 1) & 1][0] = *(const bf16x8*)(Bc + o_);
;                     fb[(s + 1) & 1][1] = *(const bf16x8*)(Bc + 32 * 128 + o_);
; #pragma unroll
;                     for (int i = 0; i < 4; ++i) fa[(s + 1) & 1][i] = *(const bf16x8*)(Ac + i * 32 * 128 + o_);
;                 }
; #pragma unroll
;                 for (int i = 0; i < 4; ++i) {
;                     acc[i][0] = __builtin_amdgcn_mfma_f32_32x32x16_bf16(fa[s & 1][i], fb[s & 1][0], acc[i][0], 0, 0, 0);
;                     acc[i][1] = __builtin_amdgcn_mfma_f32_32x32x16_bf16(fa[s & 1][i], fb[s & 1][1], acc[i][1], 0, 0, 0);
;                 }
;                 __builtin_amdgcn_sched_barrier(0);
;             }
;             if (kt + 1 < nk) asm volatile("s_waitcnt vmcnt(0)" ::: "memory");
;             __builtin_amdgcn_s_barrier();
;             cur ^= 1;
;         }
.LBB0_1160:
	v_add_u32_e32 v0, s14, v143
	s_movk_i32 s28, 0x1600
	v_mad_i64_i32 v[136:137], s[8:9], v0, s28, v[134:135]
	v_add_u32_e32 v0, s15, v143
	v_mad_i64_i32 v[138:139], s[8:9], v0, s28, v[134:135]
	v_mov_b32_e32 v2, 0
	s_mov_b64 s[8:9], 0
	s_mov_b32 s34, s13
	v_mov_b32_e32 v3, v2
	v_mov_b32_e32 v4, v2
	v_mov_b32_e32 v5, v2
	v_mov_b32_e32 v6, v2
	v_mov_b32_e32 v7, v2
	v_mov_b32_e32 v8, v2
	v_mov_b32_e32 v9, v2
	v_mov_b32_e32 v10, v2
	v_mov_b32_e32 v11, v2
	v_mov_b32_e32 v12, v2
	v_mov_b32_e32 v13, v2
	v_mov_b32_e32 v14, v2
	v_mov_b32_e32 v15, v2
	v_mov_b32_e32 v16, v2
	v_mov_b32_e32 v17, v2
	v_mov_b32_e32 v18, v2
	v_mov_b32_e32 v19, v2
	v_mov_b32_e32 v20, v2
	v_mov_b32_e32 v21, v2
	v_mov_b32_e32 v22, v2
	v_mov_b32_e32 v23, v2
	v_mov_b32_e32 v24, v2
	v_mov_b32_e32 v25, v2
	v_mov_b32_e32 v26, v2
	v_mov_b32_e32 v27, v2
	v_mov_b32_e32 v28, v2
	v_mov_b32_e32 v29, v2
	v_mov_b32_e32 v30, v2
	v_mov_b32_e32 v31, v2
	v_mov_b32_e32 v32, v2
	v_mov_b32_e32 v33, v2
	v_mov_b32_e32 v34, v2
	v_mov_b32_e32 v35, v2
	v_mov_b32_e32 v36, v2
	v_mov_b32_e32 v37, v2
	v_mov_b32_e32 v38, v2
	v_mov_b32_e32 v39, v2
	v_mov_b32_e32 v40, v2
	v_mov_b32_e32 v41, v2
	v_mov_b32_e32 v42, v2
	v_mov_b32_e32 v43, v2
	v_mov_b32_e32 v44, v2
	v_mov_b32_e32 v45, v2
	v_mov_b32_e32 v46, v2
	v_mov_b32_e32 v47, v2
	v_mov_b32_e32 v48, v2
	v_mov_b32_e32 v49, v2
	v_mov_b32_e32 v50, v2
	v_mov_b32_e32 v51, v2
	v_mov_b32_e32 v52, v2
	v_mov_b32_e32 v53, v2
	v_mov_b32_e32 v54, v2
	v_mov_b32_e32 v55, v2
	v_mov_b32_e32 v56, v2
	v_mov_b32_e32 v57, v2
	v_mov_b32_e32 v58, v2
	v_mov_b32_e32 v59, v2
	v_mov_b32_e32 v60, v2
	v_mov_b32_e32 v61, v2
	v_mov_b32_e32 v62, v2
	v_mov_b32_e32 v63, v2
	v_mov_b32_e32 v64, v2
	v_mov_b32_e32 v65, v2
	v_mov_b32_e32 v66, v2
	v_mov_b32_e32 v67, v2
	v_mov_b32_e32 v68, v2
	v_mov_b32_e32 v69, v2
	v_mov_b32_e32 v70, v2
	v_mov_b32_e32 v71, v2
	v_mov_b32_e32 v72, v2
	v_mov_b32_e32 v73, v2
	v_mov_b32_e32 v74, v2
	v_mov_b32_e32 v75, v2
	v_mov_b32_e32 v76, v2
	v_mov_b32_e32 v77, v2
	v_mov_b32_e32 v78, v2
	v_mov_b32_e32 v79, v2
	v_mov_b32_e32 v80, v2
	v_mov_b32_e32 v81, v2
	v_mov_b32_e32 v82, v2
	v_mov_b32_e32 v83, v2
	v_mov_b32_e32 v84, v2
	v_mov_b32_e32 v85, v2
	v_mov_b32_e32 v86, v2
	v_mov_b32_e32 v87, v2
	v_mov_b32_e32 v88, v2
	v_mov_b32_e32 v89, v2
	v_mov_b32_e32 v90, v2
	v_mov_b32_e32 v91, v2
	v_mov_b32_e32 v92, v2
	v_mov_b32_e32 v93, v2
	v_mov_b32_e32 v94, v2
	v_mov_b32_e32 v95, v2
	v_mov_b32_e32 v96, v2
	v_mov_b32_e32 v97, v2
	v_mov_b32_e32 v98, v2
	v_mov_b32_e32 v99, v2
	v_mov_b32_e32 v100, v2
	v_mov_b32_e32 v101, v2
	v_mov_b32_e32 v102, v2
	v_mov_b32_e32 v103, v2
	v_mov_b32_e32 v104, v2
	v_mov_b32_e32 v105, v2
	v_mov_b32_e32 v106, v2
	v_mov_b32_e32 v107, v2
	v_mov_b32_e32 v108, v2
	v_mov_b32_e32 v109, v2
	v_mov_b32_e32 v110, v2
	v_mov_b32_e32 v111, v2
	v_mov_b32_e32 v112, v2
	v_mov_b32_e32 v113, v2
	v_mov_b32_e32 v114, v2
	v_mov_b32_e32 v115, v2
	v_mov_b32_e32 v116, v2
	v_mov_b32_e32 v117, v2
	v_mov_b32_e32 v118, v2
	v_mov_b32_e32 v119, v2
	v_mov_b32_e32 v120, v2
	v_mov_b32_e32 v121, v2
	v_mov_b32_e32 v122, v2
	v_mov_b32_e32 v123, v2
	v_mov_b32_e32 v124, v2
	v_mov_b32_e32 v125, v2
	v_mov_b32_e32 v126, v2
	v_mov_b32_e32 v127, v2
	v_mov_b32_e32 v128, v2
	v_mov_b32_e32 v129, v2
	s_lshl_b32 vcc_lo, s34, 16
	v_add3_u32 v191, vcc_lo, v151, v150
	v_add_u32_e32 v191, v191, v152
	v_add3_u32 v0, vcc_lo, v149, v150
	v_add_u32_e32 v0, v0, v152
	ds_read_b128 v[156:159], v191 offset:32768
	ds_read_b128 v[160:163], v191 offset:36864
	ds_read_b128 v[192:195], v0
	ds_read_b128 v[196:199], v0 offset:4096
	ds_read_b128 v[200:203], v0 offset:8192
	ds_read_b128 v[204:207], v0 offset:12288
.LBB0_1161:
	s_mov_b32 s13, s34
	s_lshl_b32 s36, s13, 16
	s_xor_b32 s28, s36, 0x10000
	v_readfirstlane_b32 vcc_lo, v144
	s_nop 0
	s_add_u32 vcc_lo, vcc_lo, s28
	v_add3_u32 v191, s36, v151, v150
	v_add_u32_e32 v191, v191, v153
	v_add3_u32 v0, s36, v149, v150
	v_add_u32_e32 v0, v0, v153
	ds_read_b128 v[208:211], v191 offset:32768
	ds_read_b128 v[212:215], v191 offset:36864
	s_waitcnt lgkmcnt(5)
	v_mfma_f32_32x32x16_bf16 v[114:129], v[192:195], v[156:159], v[114:129]
	s_add_u32 s34, s8, 0x4100080
	s_addc_u32 s35, s9, 0
	s_mov_b32 m0, vcc_lo
	v_lshl_add_u64 v[164:165], v[136:137], 0, s[34:35]
	global_load_lds_dwordx4 v[164:165], off
	v_mfma_f32_32x32x16_bf16 v[98:113], v[192:195], v[160:163], v[98:113]
	s_add_u32 s34, s8, 0x4158080
	s_addc_u32 s35, s9, 0
	s_add_u32 m0, vcc_lo, 0x2000
	v_lshl_add_u64 v[164:165], v[136:137], 0, s[34:35]
	global_load_lds_dwordx4 v[164:165], off
	ds_read_b128 v[192:195], v0
	s_waitcnt lgkmcnt(5)
	v_mfma_f32_32x32x16_bf16 v[82:97], v[196:199], v[156:159], v[82:97]
	s_add_u32 s34, s8, 0x41b0080
	s_addc_u32 s35, s9, 0
	s_add_u32 m0, vcc_lo, 0x4000
	v_lshl_add_u64 v[164:165], v[136:137], 0, s[34:35]
	global_load_lds_dwordx4 v[164:165], off
	v_mfma_f32_32x32x16_bf16 v[66:81], v[196:199], v[160:163], v[66:81]
	s_add_u32 s34, s8, 0x4208080
	s_addc_u32 s35, s9, 0
	s_add_u32 m0, vcc_lo, 0x6000
	v_lshl_add_u64 v[164:165], v[136:137], 0, s[34:35]
	global_load_lds_dwordx4 v[164:165], off
	ds_read_b128 v[196:199], v0 offset:4096
	s_waitcnt lgkmcnt(5)
	v_mfma_f32_32x32x16_bf16 v[50:65], v[200:203], v[156:159], v[50:65]
	s_add_u32 s34, s8, 0x1900080
	s_addc_u32 s35, s9, 0
	s_add_u32 m0, vcc_lo, 0x8000
	v_lshl_add_u64 v[164:165], v[138:139], 0, s[34:35]
	global_load_lds_dwordx4 v[164:165], off
	v_mfma_f32_32x32x16_bf16 v[34:49], v[200:203], v[160:163], v[34:49]
	s_add_u32 s34, s8, 0x1958080
	s_addc_u32 s35, s9, 0
	s_add_u32 m0, vcc_lo, 0xa000
	v_lshl_add_u64 v[164:165], v[138:139], 0, s[34:35]
	global_load_lds_dwordx4 v[164:165], off
	ds_read_b128 v[200:203], v0 offset:8192
	s_waitcnt lgkmcnt(5)
; template <int EPI, int AMAP, int KOFFMODE, int K>
; __device__ __forceinline__ void gemm_phase(unsigned char* smem, const bf16_t* A, int lda, const bf16_t* Bt, int NT, const EpiArgs& ea) {
;     ...
;         for (int kt = 0; kt < nk; ++kt) {
;             if (kt + 1 < nk) GEMM_DMA(m0, n0, kt + 1, cur ^ 1);
;             else if (have_next) GEMM_DMA(m0n, n0n, 0, cur ^ 1);
;             const unsigned char* Ac = smem + cur * STGB + (wm * 128 + l31) * 128;
;             const unsigned char* Bc = smem + cur * STGB + 32768 + (wn * 64 + l31) * 128;
;             bf16x8 fa[2][4], fb[2][2];
;             fb[0][0] = *(const bf16x8*)(Bc + (((0) ^ yz) & 7) * 16);
;             fb[0][1] = *(const bf16x8*)(Bc + 32 * 128 + (((0) ^ yz) & 7) * 16);
; #pragma unroll
;             for (int i = 0; i < 4; ++i) fa[0][i] = *(const bf16x8*)(Ac + i * 32 * 128 + (((0) ^ yz) & 7) * 16);
; #pragma unroll
;             for (int s = 0; s < 4; ++s) {
;                 if (s < 3) {
;                     const int o_ = (((2 * (s + 1)) ^ yz) & 7) * 16;
;                     fb[(s + 1) & 1][0] = *(const bf16x8*)(Bc + o_);
;                     fb[(s + 1) & 1][1] = *(const bf16x8*)(Bc + 32 * 128 + o_);
; #pragma unroll
;                     for (int i = 0; i < 4; ++i) fa[(s + 1) & 1][i] = *(const bf16x8*)(Ac + i * 32 * 128 + o_);
;                 }
; #pragma unroll
;                 for (int i = 0; i < 4; ++i) {
;                     acc[i][0] = __builtin_amdgcn_mfma_f32_32x32x16_bf16(fa[s & 1][i], fb[s & 1][0], acc[i][0], 0, 0, 0);
;                     acc[i][1] = __builtin_amdgcn_mfma_f32_32x32x16_bf16(fa[s & 1][i], fb[s & 1][1], acc[i][1], 0, 0, 0);
;                 }
;                 __builtin_amdgcn_sched_barrier(0);
;             }
;             if (kt + 1 < nk) asm volatile("s_waitcnt vmcnt(0)" ::: "memory");
;             __builtin_amdgcn_s_barrier();
;             cur ^= 1;
;         }
	v_mfma_f32_32x32x16_bf16 v[18:33], v[204:207], v[156:159], v[18:33]
	s_add_u32 s34, s8, 0x19b0080
	s_addc_u32 s35, s9, 0
	s_add_u32 m0, vcc_lo, 0xc000
	v_lshl_add_u64 v[164:165], v[138:139], 0, s[34:35]
	global_load_lds_dwordx4 v[164:165], off
	v_mfma_f32_32x32x16_bf16 v[2:17], v[204:207], v[160:163], v[2:17]
	s_add_u32 s34, s8, 0x1a08080
	s_addc_u32 s35, s9, 0
	s_add_u32 m0, vcc_lo, 0xe000
	v_lshl_add_u64 v[164:165], v[138:139], 0, s[34:35]
	global_load_lds_dwordx4 v[164:165], off
	ds_read_b128 v[204:207], v0 offset:12288
	v_add3_u32 v191, s36, v151, v150
	v_add_u32_e32 v191, v191, v154
	v_add3_u32 v0, s36, v149, v150
	v_add_u32_e32 v0, v0, v154
	ds_read_b128 v[156:159], v191 offset:32768
	ds_read_b128 v[160:163], v191 offset:36864
	s_waitcnt lgkmcnt(5)
	v_mfma_f32_32x32x16_bf16 v[114:129], v[192:195], v[208:211], v[114:129]
	v_mfma_f32_32x32x16_bf16 v[98:113], v[192:195], v[212:215], v[98:113]
	ds_read_b128 v[192:195], v0
	s_waitcnt lgkmcnt(5)
	v_mfma_f32_32x32x16_bf16 v[82:97], v[196:199], v[208:211], v[82:97]
	v_mfma_f32_32x32x16_bf16 v[66:81], v[196:199], v[212:215], v[66:81]
	ds_read_b128 v[196:199], v0 offset:4096
	s_waitcnt lgkmcnt(5)
	v_mfma_f32_32x32x16_bf16 v[50:65], v[200:203], v[208:211], v[50:65]
	v_mfma_f32_32x32x16_bf16 v[34:49], v[200:203], v[212:215], v[34:49]
	ds_read_b128 v[200:203], v0 offset:8192
	s_waitcnt lgkmcnt(5)
	v_mfma_f32_32x32x16_bf16 v[18:33], v[204:207], v[208:211], v[18:33]
	v_mfma_f32_32x32x16_bf16 v[2:17], v[204:207], v[212:215], v[2:17]
	ds_read_b128 v[204:207], v0 offset:12288
	v_add3_u32 v191, s36, v151, v150
	v_add_u32_e32 v191, v191, v155
	v_add3_u32 v0, s36, v149, v150
	v_add_u32_e32 v0, v0, v155
	ds_read_b128 v[208:211], v191 offset:32768
	ds_read_b128 v[212:215], v191 offset:36864
	s_waitcnt lgkmcnt(5)
	v_mfma_f32_32x32x16_bf16 v[114:129], v[192:195], v[156:159], v[114:129]
	v_mfma_f32_32x32x16_bf16 v[98:113], v[192:195], v[160:163], v[98:113]
	ds_read_b128 v[192:195], v0
	s_waitcnt lgkmcnt(5)
	v_mfma_f32_32x32x16_bf16 v[82:97], v[196:199], v[156:159], v[82:97]
	v_mfma_f32_32x32x16_bf16 v[66:81], v[196:199], v[160:163], v[66:81]
	ds_read_b128 v[196:199], v0 offset:4096
	s_waitcnt lgkmcnt(5)
	v_mfma_f32_32x32x16_bf16 v[50:65], v[200:203], v[156:159], v[50:65]
	v_mfma_f32_32x32x16_bf16 v[34:49], v[200:203], v[160:163], v[34:49]
	ds_read_b128 v[200:203], v0 offset:8192
	s_waitcnt lgkmcnt(5)
	v_mfma_f32_32x32x16_bf16 v[18:33], v[204:207], v[156:159], v[18:33]
	v_mfma_f32_32x32x16_bf16 v[2:17], v[204:207], v[160:163], v[2:17]
	ds_read_b128 v[204:207], v0 offset:12288
	s_waitcnt lgkmcnt(3)
	v_mfma_f32_32x32x16_bf16 v[114:129], v[192:195], v[208:211], v[114:129]
	v_mfma_f32_32x32x16_bf16 v[98:113], v[192:195], v[212:215], v[98:113]
	s_waitcnt lgkmcnt(0)
	s_waitcnt vmcnt(0)
	s_barrier
	v_add3_u32 v191, s28, v151, v150
	v_add_u32_e32 v191, v191, v152
	v_add3_u32 v0, s28, v149, v150
	v_add_u32_e32 v0, v0, v152
	ds_read_b128 v[156:159], v191 offset:32768
	ds_read_b128 v[160:163], v191 offset:36864
	ds_read_b128 v[192:195], v0
	v_mfma_f32_32x32x16_bf16 v[82:97], v[196:199], v[208:211], v[82:97]
	v_mfma_f32_32x32x16_bf16 v[66:81], v[196:199], v[212:215], v[66:81]
	ds_read_b128 v[196:199], v0 offset:4096
	v_mfma_f32_32x32x16_bf16 v[50:65], v[200:203], v[208:211], v[50:65]
	v_mfma_f32_32x32x16_bf16 v[34:49], v[200:203], v[212:215], v[34:49]
	ds_read_b128 v[200:203], v0 offset:8192
	v_mfma_f32_32x32x16_bf16 v[18:33], v[204:207], v[208:211], v[18:33]
	v_mfma_f32_32x32x16_bf16 v[2:17], v[204:207], v[212:215], v[2:17]
	ds_read_b128 v[204:207], v0 offset:12288
	s_xor_b32 s34, s13, 1
	s_add_u32 s8, s8, 0x80
	s_addc_u32 s9, s9, 0
	s_cmpk_eq_i32 s8, 0x1580
	s_cbranch_scc0 .LBB0_1161
	s_waitcnt lgkmcnt(0)
	s_andn2_b64 vcc, exec, s[2:3]
	s_lshl_b32 s2, s34, 16
	s_cbranch_vccnz .LBB0_1153
	v_add_u32_e32 v0, s12, v143
	v_add_u32_e32 v136, s11, v143
	s_movk_i32 s3, 0x1600
	v_mad_i64_i32 v[136:137], s[8:9], v136, s3, v[132:133]
	v_mad_i64_i32 v[138:139], s[8:9], v0, s3, v[130:131]
	s_xor_b32 s3, s2, 0x10000
	v_add_u32_e32 v0, s3, v144
	v_add_u32_e32 v156, 0x8000, v0
	v_readfirstlane_b32 s3, v0
	s_mov_b32 m0, s3
	v_readfirstlane_b32 s3, v156
	v_add_u32_e32 v158, 0x2000, v0
	global_load_lds_dwordx4 v[138:139], off
	s_mov_b32 m0, s3
	s_mov_b64 s[8:9], 0x58000
	v_readfirstlane_b32 s3, v158
	v_add_u32_e32 v158, 0xa000, v0
	global_load_lds_dwordx4 v[136:137], off
	v_lshl_add_u64 v[156:157], v[138:139], 0, s[8:9]
	s_mov_b32 m0, s3
	v_readfirstlane_b32 s3, v158
	v_add_u32_e32 v158, 0x4000, v0
	global_load_lds_dwordx4 v[156:157], off
	v_lshl_add_u64 v[156:157], v[136:137], 0, s[8:9]
	s_mov_b32 m0, s3
	s_mov_b64 s[8:9], 0xb0000
	v_readfirstlane_b32 s3, v158
	v_add_u32_e32 v158, 0xc000, v0
	global_load_lds_dwordx4 v[156:157], off
	v_lshl_add_u64 v[156:157], v[138:139], 0, s[8:9]
	s_mov_b32 m0, s3
	v_readfirstlane_b32 s3, v158
	global_load_lds_dwordx4 v[156:157], off
	v_lshl_add_u64 v[156:157], v[136:137], 0, s[8:9]
	s_mov_b32 m0, s3
	s_mov_b64 s[8:9], 0x108000
	global_load_lds_dwordx4 v[156:157], off
	v_add_u32_e32 v156, 0x6000, v0
	v_add_u32_e32 v0, 0xe000, v0
	v_readfirstlane_b32 s3, v156
	v_lshl_add_u64 v[138:139], v[138:139], 0, s[8:9]
	s_mov_b32 m0, s3
	v_readfirstlane_b32 s3, v0
	global_load_lds_dwordx4 v[138:139], off
	v_lshl_add_u64 v[136:137], v[136:137], 0, s[8:9]
	s_mov_b32 m0, s3
	s_nop 0
	global_load_lds_dwordx4 v[136:137], off
	s_branch .LBB0_1153
